# FF1: bias2 row loaded at unit start into spare VGPRs; epilogue copies it and no longer waits vmcnt(0)
# baseline (speedup 1.0000x reference)
.LBB0_567:
	s_ashr_i32 s19, s18, 31
	s_lshl_b64 s[20:21], s[18:19], 19
	s_add_u32 s20, s14, s20
	s_addc_u32 s21, s15, s21
	s_and_b64 s[22:23], s[4:5], exec
	s_cselect_b32 s19, s21, s29
	s_cselect_b32 s27, s20, s28
	s_ashr_i32 s17, s16, 31
	s_lshl_b64 s[22:23], s[16:17], 19
	s_add_u32 s22, s33, s22
	s_addc_u32 s23, s34, s23
	s_and_b64 s[38:39], s[4:5], exec
	s_cselect_b32 s17, s23, s37
	s_cselect_b32 s73, s22, s36
	s_add_u32 s74, s36, 0x100
	s_addc_u32 s75, s37, 0
	s_mov_b32 s76, -2
	v_mov_b32_e32 v232, v165
	s_lshl_b32 s98, s72, 8
	s_or_b32 s98, s98, s66
	v_lshlrev_b32_e32 v233, 3, v232
	v_add_u32_e32 v232, s98, v233
	s_lshl_b32 s98, s26, 8
	s_and_b32 s98, s98, 0xfffff000
	s_ashr_i32 s99, s98, 31
	s_lshl_b64 s[98:99], s[98:99], 2
	s_add_u32 s98, s59, s98
	s_addc_u32 s99, s61, s99
	v_ashrrev_i32_e32 v233, 31, v232
	v_lshl_add_u64 v[232:233], v[232:233], 2, s[98:99]
	global_load_dwordx4 v[228:231], v[232:233], off
	global_load_dwordx4 v[224:227], v[232:233], off offset:16
	global_load_dwordx4 v[220:223], v[232:233], off offset:512
	global_load_dwordx4 v[216:219], v[232:233], off offset:528
	ds_read_b128 v[128:131], v167
	ds_read_b128 v[132:135], v167 offset:1024
	ds_read_b128 v[136:139], v167 offset:2048
	ds_read_b128 v[140:143], v167 offset:3072
	ds_read_b128 v[160:163], v168
	ds_read_b128 v[170:173], v168 offset:1024
	ds_read_b128 v[174:177], v168 offset:2048
	ds_read_b128 v[178:181], v168 offset:3072
	s_add_u32 s36, s28, 0x10000
	s_addc_u32 s37, s29, 0
	s_cmp_eq_u32 s76, 12
	s_cselect_b32 s42, s27, s36
	s_cselect_b32 s43, s19, s37
	s_cselect_b32 s40, s73, s74
	s_cselect_b32 s41, s17, s75
	s_add_u32 s38, s42, 0x8000
	s_addc_u32 s39, s43, 0
	s_add_i32 m0, s44, 0xc000
	ds_read_b128 v[182:185], v169
	ds_read_b128 v[186:189], v169 offset:1024
	ds_read_b128 v[190:193], v169 offset:2048
	ds_read_b128 v[194:197], v169 offset:3072
	ds_read_b128 v[198:201], v169 offset:4096
	ds_read_b128 v[202:205], v169 offset:5120
	ds_read_b128 v[206:209], v169 offset:6144
	ds_read_b128 v[210:213], v169 offset:7168
	global_load_lds_dwordx4 v152, s[28:29]
	s_add_i32 m0, s44, 0xe000
	s_nop 0
	global_load_lds_dwordx4 v154, s[28:29]
	s_waitcnt vmcnt(8)
	s_waitcnt lgkmcnt(0)
	s_setprio 1
	s_barrier
	v_mfma_f32_16x16x32_bf16 v[124:127], v[128:131], v[182:185], 0
	v_mfma_f32_16x16x32_bf16 v[120:123], v[136:139], v[182:185], 0
	v_mfma_f32_16x16x32_bf16 v[116:119], v[128:131], v[190:193], 0
	v_mfma_f32_16x16x32_bf16 v[112:115], v[136:139], v[190:193], 0
	v_mfma_f32_16x16x32_bf16 v[92:95], v[128:131], v[198:201], 0
	v_mfma_f32_16x16x32_bf16 v[88:91], v[136:139], v[198:201], 0
	v_mfma_f32_16x16x32_bf16 v[76:79], v[128:131], v[206:209], 0
	v_mfma_f32_16x16x32_bf16 v[72:75], v[136:139], v[206:209], 0
	v_mfma_f32_16x16x32_bf16 v[124:127], v[132:135], v[186:189], v[124:127]
	v_mfma_f32_16x16x32_bf16 v[120:123], v[140:143], v[186:189], v[120:123]
	v_mfma_f32_16x16x32_bf16 v[116:119], v[132:135], v[194:197], v[116:119]
	v_mfma_f32_16x16x32_bf16 v[112:115], v[140:143], v[194:197], v[112:115]
	v_mfma_f32_16x16x32_bf16 v[92:95], v[132:135], v[202:205], v[92:95]
	v_mfma_f32_16x16x32_bf16 v[88:91], v[140:143], v[202:205], v[88:91]
	v_mfma_f32_16x16x32_bf16 v[76:79], v[132:135], v[210:213], v[76:79]
	v_mfma_f32_16x16x32_bf16 v[72:75], v[140:143], v[210:213], v[72:75]
	v_mfma_f32_16x16x32_bf16 v[108:111], v[160:163], v[182:185], 0
	v_mfma_f32_16x16x32_bf16 v[104:107], v[174:177], v[182:185], 0
	v_mfma_f32_16x16x32_bf16 v[100:103], v[160:163], v[190:193], 0
	v_mfma_f32_16x16x32_bf16 v[96:99], v[174:177], v[190:193], 0
	v_mfma_f32_16x16x32_bf16 v[84:87], v[160:163], v[198:201], 0
	v_mfma_f32_16x16x32_bf16 v[80:83], v[174:177], v[198:201], 0
	v_mfma_f32_16x16x32_bf16 v[68:71], v[160:163], v[206:209], 0
	v_mfma_f32_16x16x32_bf16 v[64:67], v[174:177], v[206:209], 0
	v_mfma_f32_16x16x32_bf16 v[108:111], v[170:173], v[186:189], v[108:111]
	v_mfma_f32_16x16x32_bf16 v[104:107], v[178:181], v[186:189], v[104:107]
	v_mfma_f32_16x16x32_bf16 v[100:103], v[170:173], v[194:197], v[100:103]
	v_mfma_f32_16x16x32_bf16 v[96:99], v[178:181], v[194:197], v[96:99]
	v_mfma_f32_16x16x32_bf16 v[84:87], v[170:173], v[202:205], v[84:87]
	v_mfma_f32_16x16x32_bf16 v[80:83], v[178:181], v[202:205], v[80:83]
	v_mfma_f32_16x16x32_bf16 v[68:71], v[170:173], v[210:213], v[68:71]
	v_mfma_f32_16x16x32_bf16 v[64:67], v[178:181], v[210:213], v[64:67]
	s_barrier
	s_setprio 0
	s_add_i32 s28, s70, s35
	s_mov_b32 m0, s28
	ds_read_b128 v[182:185], v169 offset:16384
	ds_read_b128 v[186:189], v169 offset:17408
	ds_read_b128 v[190:193], v169 offset:18432
	ds_read_b128 v[194:197], v169 offset:19456
	ds_read_b128 v[198:201], v169 offset:20480
	ds_read_b128 v[202:205], v169 offset:21504
	ds_read_b128 v[206:209], v169 offset:22528
	ds_read_b128 v[210:213], v169 offset:23552
	global_load_lds_dwordx4 v148, s[40:41]
	s_add_i32 m0, s28, 0x2000
	s_add_u32 s28, s40, 0x40000
	s_addc_u32 s29, s41, 0
	s_add_i32 s77, s71, s35
	global_load_lds_dwordx4 v144, s[40:41]
	s_mov_b32 m0, s77
	s_nop 0
	global_load_lds_dwordx4 v148, s[28:29]
	s_add_i32 m0, s77, 0x2000
	s_nop 0
	global_load_lds_dwordx4 v144, s[28:29]
	s_mov_b32 m0, s44
	s_nop 0
	global_load_lds_dwordx4 v150, s[42:43]
	s_mov_b32 m0, s45
	s_nop 0
	global_load_lds_dwordx4 v146, s[42:43]
	s_waitcnt vmcnt(8)
	s_waitcnt lgkmcnt(0)
	s_setprio 1
	s_barrier
	v_mfma_f32_16x16x32_bf16 v[60:63], v[128:131], v[182:185], 0
	v_mfma_f32_16x16x32_bf16 v[56:59], v[136:139], v[182:185], 0
	v_mfma_f32_16x16x32_bf16 v[44:47], v[128:131], v[190:193], 0
	v_mfma_f32_16x16x32_bf16 v[40:43], v[136:139], v[190:193], 0
	v_mfma_f32_16x16x32_bf16 v[28:31], v[128:131], v[198:201], 0
	v_mfma_f32_16x16x32_bf16 v[24:27], v[136:139], v[198:201], 0
	v_mfma_f32_16x16x32_bf16 v[12:15], v[128:131], v[206:209], 0
	v_mfma_f32_16x16x32_bf16 v[8:11], v[136:139], v[206:209], 0
	v_mfma_f32_16x16x32_bf16 v[60:63], v[132:135], v[186:189], v[60:63]
	v_mfma_f32_16x16x32_bf16 v[56:59], v[140:143], v[186:189], v[56:59]
	v_mfma_f32_16x16x32_bf16 v[44:47], v[132:135], v[194:197], v[44:47]
	v_mfma_f32_16x16x32_bf16 v[40:43], v[140:143], v[194:197], v[40:43]
	v_mfma_f32_16x16x32_bf16 v[28:31], v[132:135], v[202:205], v[28:31]
	v_mfma_f32_16x16x32_bf16 v[24:27], v[140:143], v[202:205], v[24:27]
	v_mfma_f32_16x16x32_bf16 v[12:15], v[132:135], v[210:213], v[12:15]
	v_mfma_f32_16x16x32_bf16 v[8:11], v[140:143], v[210:213], v[8:11]
	v_mfma_f32_16x16x32_bf16 v[52:55], v[160:163], v[182:185], 0
	v_mfma_f32_16x16x32_bf16 v[48:51], v[174:177], v[182:185], 0
	v_mfma_f32_16x16x32_bf16 v[36:39], v[160:163], v[190:193], 0
	v_mfma_f32_16x16x32_bf16 v[32:35], v[174:177], v[190:193], 0
	v_mfma_f32_16x16x32_bf16 v[20:23], v[160:163], v[198:201], 0
	v_mfma_f32_16x16x32_bf16 v[16:19], v[174:177], v[198:201], 0
	v_mfma_f32_16x16x32_bf16 v[4:7], v[160:163], v[206:209], 0
	v_mfma_f32_16x16x32_bf16 v[0:3], v[174:177], v[206:209], 0
	v_mfma_f32_16x16x32_bf16 v[52:55], v[170:173], v[186:189], v[52:55]
	v_mfma_f32_16x16x32_bf16 v[48:51], v[178:181], v[186:189], v[48:51]
	v_mfma_f32_16x16x32_bf16 v[36:39], v[170:173], v[194:197], v[36:39]
	v_mfma_f32_16x16x32_bf16 v[32:35], v[178:181], v[194:197], v[32:35]
	v_mfma_f32_16x16x32_bf16 v[20:23], v[170:173], v[202:205], v[20:23]
	v_mfma_f32_16x16x32_bf16 v[16:19], v[178:181], v[202:205], v[16:19]
	v_mfma_f32_16x16x32_bf16 v[4:7], v[170:173], v[210:213], v[4:7]
	v_mfma_f32_16x16x32_bf16 v[0:3], v[178:181], v[210:213], v[0:3]
	s_barrier
	s_setprio 0
	s_add_i32 s77, 0, 0x18000
	s_add_i32 s78, 0, 0x1c000
	v_add_u32_e32 v140, s77, v166
	v_add_u32_e32 v178, s78, v166
	ds_read_b128 v[128:131], v140
	ds_read_b128 v[132:135], v140 offset:1024
	ds_read_b128 v[136:139], v140 offset:2048
	ds_read_b128 v[140:143], v140 offset:3072
	ds_read_b128 v[160:163], v178
	ds_read_b128 v[170:173], v178 offset:1024
	ds_read_b128 v[174:177], v178 offset:2048
	ds_read_b128 v[178:181], v178 offset:3072
	s_add_u32 s28, s42, 0x2000
	s_addc_u32 s29, s43, 0
	s_mov_b32 m0, s46
	ds_read_b128 v[182:185], v169 offset:32768
	ds_read_b128 v[186:189], v169 offset:33792
	ds_read_b128 v[190:193], v169 offset:34816
	ds_read_b128 v[194:197], v169 offset:35840
	ds_read_b128 v[198:201], v169 offset:36864
	ds_read_b128 v[202:205], v169 offset:37888
	ds_read_b128 v[206:209], v169 offset:38912
	ds_read_b128 v[210:213], v169 offset:39936
	global_load_lds_dwordx4 v150, s[28:29]
	s_mov_b32 m0, s47
	s_nop 0
	global_load_lds_dwordx4 v146, s[28:29]
	s_waitcnt vmcnt(8)
	s_waitcnt lgkmcnt(0)
	s_setprio 1
	s_barrier
	v_mfma_f32_16x16x32_bf16 v[124:127], v[128:131], v[182:185], v[124:127]
	v_mfma_f32_16x16x32_bf16 v[120:123], v[136:139], v[182:185], v[120:123]
	v_mfma_f32_16x16x32_bf16 v[116:119], v[128:131], v[190:193], v[116:119]
	v_mfma_f32_16x16x32_bf16 v[112:115], v[136:139], v[190:193], v[112:115]
	v_mfma_f32_16x16x32_bf16 v[92:95], v[128:131], v[198:201], v[92:95]
	v_mfma_f32_16x16x32_bf16 v[88:91], v[136:139], v[198:201], v[88:91]
	v_mfma_f32_16x16x32_bf16 v[76:79], v[128:131], v[206:209], v[76:79]
	v_mfma_f32_16x16x32_bf16 v[72:75], v[136:139], v[206:209], v[72:75]
	v_mfma_f32_16x16x32_bf16 v[124:127], v[132:135], v[186:189], v[124:127]
	v_mfma_f32_16x16x32_bf16 v[120:123], v[140:143], v[186:189], v[120:123]
	v_mfma_f32_16x16x32_bf16 v[116:119], v[132:135], v[194:197], v[116:119]
	v_mfma_f32_16x16x32_bf16 v[112:115], v[140:143], v[194:197], v[112:115]
	v_mfma_f32_16x16x32_bf16 v[92:95], v[132:135], v[202:205], v[92:95]
	v_mfma_f32_16x16x32_bf16 v[88:91], v[140:143], v[202:205], v[88:91]
	v_mfma_f32_16x16x32_bf16 v[76:79], v[132:135], v[210:213], v[76:79]
	v_mfma_f32_16x16x32_bf16 v[72:75], v[140:143], v[210:213], v[72:75]
	v_mfma_f32_16x16x32_bf16 v[108:111], v[160:163], v[182:185], v[108:111]
	v_mfma_f32_16x16x32_bf16 v[104:107], v[174:177], v[182:185], v[104:107]
	v_mfma_f32_16x16x32_bf16 v[100:103], v[160:163], v[190:193], v[100:103]
	v_mfma_f32_16x16x32_bf16 v[96:99], v[174:177], v[190:193], v[96:99]
	v_mfma_f32_16x16x32_bf16 v[84:87], v[160:163], v[198:201], v[84:87]
	v_mfma_f32_16x16x32_bf16 v[80:83], v[174:177], v[198:201], v[80:83]
	v_mfma_f32_16x16x32_bf16 v[68:71], v[160:163], v[206:209], v[68:71]
	v_mfma_f32_16x16x32_bf16 v[64:67], v[174:177], v[206:209], v[64:67]
	v_mfma_f32_16x16x32_bf16 v[108:111], v[170:173], v[186:189], v[108:111]
	v_mfma_f32_16x16x32_bf16 v[104:107], v[178:181], v[186:189], v[104:107]
	v_mfma_f32_16x16x32_bf16 v[100:103], v[170:173], v[194:197], v[100:103]
	v_mfma_f32_16x16x32_bf16 v[96:99], v[178:181], v[194:197], v[96:99]
	v_mfma_f32_16x16x32_bf16 v[84:87], v[170:173], v[202:205], v[84:87]
	v_mfma_f32_16x16x32_bf16 v[80:83], v[178:181], v[202:205], v[80:83]
	v_mfma_f32_16x16x32_bf16 v[68:71], v[170:173], v[210:213], v[68:71]
	v_mfma_f32_16x16x32_bf16 v[64:67], v[178:181], v[210:213], v[64:67]
	s_barrier
	s_setprio 0
	s_add_u32 s98, s40, s12
	s_addc_u32 s99, s41, s13
	s_add_i32 s28, s77, s35
	s_mov_b32 m0, s28
	ds_read_b128 v[182:185], v169 offset:49152
	ds_read_b128 v[186:189], v169 offset:50176
	ds_read_b128 v[190:193], v169 offset:51200
	ds_read_b128 v[194:197], v169 offset:52224
	ds_read_b128 v[198:201], v169 offset:53248
	ds_read_b128 v[202:205], v169 offset:54272
	ds_read_b128 v[206:209], v169 offset:55296
	ds_read_b128 v[210:213], v169 offset:56320
	global_load_lds_dwordx4 v148, s[98:99]
	s_add_i32 m0, s28, 0x2000
	s_add_u32 s28, s40, 0x40080
	s_addc_u32 s29, s41, 0
	s_add_i32 s40, s78, s35
	global_load_lds_dwordx4 v144, s[98:99]
	s_mov_b32 m0, s40
	s_nop 0
	global_load_lds_dwordx4 v148, s[28:29]
	s_add_i32 m0, s40, 0x2000
	s_nop 0
	global_load_lds_dwordx4 v144, s[28:29]
	s_mov_b32 m0, s68
	s_nop 0
	global_load_lds_dwordx4 v150, s[38:39]
	s_mov_b32 m0, s69
	s_nop 0
	global_load_lds_dwordx4 v146, s[38:39]
	s_waitcnt vmcnt(8)
	s_waitcnt lgkmcnt(0)
	s_setprio 1
	s_barrier
	v_mfma_f32_16x16x32_bf16 v[60:63], v[128:131], v[182:185], v[60:63]
	v_mfma_f32_16x16x32_bf16 v[56:59], v[136:139], v[182:185], v[56:59]
	v_mfma_f32_16x16x32_bf16 v[44:47], v[128:131], v[190:193], v[44:47]
	v_mfma_f32_16x16x32_bf16 v[40:43], v[136:139], v[190:193], v[40:43]
	v_mfma_f32_16x16x32_bf16 v[28:31], v[128:131], v[198:201], v[28:31]
	v_mfma_f32_16x16x32_bf16 v[24:27], v[136:139], v[198:201], v[24:27]
	v_mfma_f32_16x16x32_bf16 v[12:15], v[128:131], v[206:209], v[12:15]
	v_mfma_f32_16x16x32_bf16 v[8:11], v[136:139], v[206:209], v[8:11]
	v_mfma_f32_16x16x32_bf16 v[60:63], v[132:135], v[186:189], v[60:63]
	v_mfma_f32_16x16x32_bf16 v[56:59], v[140:143], v[186:189], v[56:59]
	v_mfma_f32_16x16x32_bf16 v[44:47], v[132:135], v[194:197], v[44:47]
	v_mfma_f32_16x16x32_bf16 v[40:43], v[140:143], v[194:197], v[40:43]
	v_mfma_f32_16x16x32_bf16 v[28:31], v[132:135], v[202:205], v[28:31]
	v_mfma_f32_16x16x32_bf16 v[24:27], v[140:143], v[202:205], v[24:27]
	v_mfma_f32_16x16x32_bf16 v[12:15], v[132:135], v[210:213], v[12:15]
	v_mfma_f32_16x16x32_bf16 v[8:11], v[140:143], v[210:213], v[8:11]
	v_mfma_f32_16x16x32_bf16 v[52:55], v[160:163], v[182:185], v[52:55]
	v_mfma_f32_16x16x32_bf16 v[48:51], v[174:177], v[182:185], v[48:51]
	v_mfma_f32_16x16x32_bf16 v[36:39], v[160:163], v[190:193], v[36:39]
	v_mfma_f32_16x16x32_bf16 v[32:35], v[174:177], v[190:193], v[32:35]
	v_mfma_f32_16x16x32_bf16 v[20:23], v[160:163], v[198:201], v[20:23]
	v_mfma_f32_16x16x32_bf16 v[16:19], v[174:177], v[198:201], v[16:19]
	v_mfma_f32_16x16x32_bf16 v[4:7], v[160:163], v[206:209], v[4:7]
	v_mfma_f32_16x16x32_bf16 v[0:3], v[174:177], v[206:209], v[0:3]
	v_mfma_f32_16x16x32_bf16 v[52:55], v[170:173], v[186:189], v[52:55]
	v_mfma_f32_16x16x32_bf16 v[48:51], v[178:181], v[186:189], v[48:51]
	v_mfma_f32_16x16x32_bf16 v[36:39], v[170:173], v[194:197], v[36:39]
	v_mfma_f32_16x16x32_bf16 v[32:35], v[178:181], v[194:197], v[32:35]
	v_mfma_f32_16x16x32_bf16 v[20:23], v[170:173], v[202:205], v[20:23]
	v_mfma_f32_16x16x32_bf16 v[16:19], v[178:181], v[202:205], v[16:19]
	v_mfma_f32_16x16x32_bf16 v[4:7], v[170:173], v[210:213], v[4:7]
	v_mfma_f32_16x16x32_bf16 v[0:3], v[178:181], v[210:213], v[0:3]
	s_barrier
	s_setprio 0
	s_add_i32 s76, s76, 2
	s_add_u32 s74, s74, 0x100
	s_addc_u32 s75, s75, 0
	s_cmp_gt_u32 s76, 13
	s_mov_b64 s[28:29], s[36:37]

.LBB0_571:
	v_mov_b32_e32 v161, v164
	v_mov_b32_e32 v128, v165
	s_lshl_b32 s17, s72, 8
	s_or_b32 s17, s17, s66
	v_lshlrev_b32_e32 v160, 3, v128
	v_add_u32_e32 v128, s17, v160
	s_lshl_b32 s17, s26, 8
	s_and_b32 s28, s17, 0xfffff000
	s_ashr_i32 s29, s28, 31
	s_lshl_b64 s[28:29], s[28:29], 2
	s_add_u32 s28, s59, s28
	s_addc_u32 s29, s61, s29
	v_ashrrev_i32_e32 v129, 31, v128
	v_lshl_add_u64 v[128:129], v[128:129], 2, s[28:29]
	v_mov_b64_e32 v[140:141], v[228:229]
	v_mov_b64_e32 v[142:143], v[230:231]
	v_mov_b64_e32 v[136:137], v[224:225]
	v_mov_b64_e32 v[138:139], v[226:227]
	v_mov_b64_e32 v[132:133], v[220:221]
	v_mov_b64_e32 v[134:135], v[222:223]
	v_mov_b64_e32 v[128:129], v[216:217]
	v_mov_b64_e32 v[130:131], v[218:219]
	v_add_u32_e32 v162, s57, v161
	v_lshl_add_u32 v170, v162, 2, 0
	s_lshl_b32 s17, s72, 3
	v_add_u32_e32 v170, 0x22400, v170
	s_or_b32 s28, s17, s56
	s_ashr_i32 s27, s26, 31
	ds_read2_b32 v[172:173], v170 offset1:16
	s_ashr_i32 s29, s28, 31
	s_lshl_b64 s[26:27], s[26:27], 21
	s_lshl_b64 s[28:29], s[28:29], 14
	s_add_u32 s17, s64, s26
	s_addc_u32 s19, s65, s27
	v_ashrrev_i32_e32 v163, 31, v162
	s_add_u32 s26, s17, s28
	v_lshlrev_b64 v[162:163], 6, v[162:163]
	s_addc_u32 s27, s19, s29
	v_ashrrev_i32_e32 v161, 31, v160
	v_lshl_add_u64 v[162:163], s[26:27], 0, v[162:163]
	s_waitcnt lgkmcnt(0)
	v_mov_b32_e32 v174, v173
	v_lshl_add_u64 v[160:161], v[160:161], 1, v[162:163]
	v_add_co_u32_e32 v162, vcc, s49, v160
	v_pk_fma_f32 v[126:127], v[126:127], v[172:173], v[142:143] op_sel_hi:[1,0,1]
	v_pk_fma_f32 v[124:125], v[124:125], v[172:173], v[140:141] op_sel_hi:[1,0,1]
	v_pk_fma_f32 v[122:123], v[122:123], v[172:173], v[138:139] op_sel_hi:[1,0,1]
	v_pk_fma_f32 v[120:121], v[120:121], v[172:173], v[136:137] op_sel_hi:[1,0,1]
	v_pk_fma_f32 v[110:111], v[110:111], v[172:173], v[134:135] op_sel_hi:[1,0,1]
	v_pk_fma_f32 v[108:109], v[108:109], v[172:173], v[132:133] op_sel_hi:[1,0,1]
	v_pk_fma_f32 v[106:107], v[106:107], v[172:173], v[130:131] op_sel_hi:[1,0,1]
	v_pk_fma_f32 v[104:105], v[104:105], v[172:173], v[128:129] op_sel_hi:[1,0,1]
	v_max_f32_e32 v124, 0, v124
	v_max_f32_e32 v120, 0, v120
	v_max_f32_e32 v125, 0, v125
	v_max_f32_e32 v121, 0, v121
	v_max_f32_e32 v126, 0, v126
	v_max_f32_e32 v122, 0, v122
	v_max_f32_e32 v127, 0, v127
	v_max_f32_e32 v123, 0, v123
	v_max_f32_e32 v108, 0, v108
	v_max_f32_e32 v104, 0, v104
	v_max_f32_e32 v109, 0, v109
	v_max_f32_e32 v105, 0, v105
	v_max_f32_e32 v110, 0, v110
	v_max_f32_e32 v106, 0, v106
	v_max_f32_e32 v111, 0, v111
	v_max_f32_e32 v107, 0, v107
	v_pk_mul_f32 v[124:125], v[124:125], v[124:125]
	v_pk_mul_f32 v[120:121], v[120:121], v[120:121]
	v_pk_mul_f32 v[126:127], v[126:127], v[126:127]
	v_pk_mul_f32 v[122:123], v[122:123], v[122:123]
	v_pk_mul_f32 v[108:109], v[108:109], v[108:109]
	v_pk_mul_f32 v[172:173], v[104:105], v[104:105]
	v_pk_mul_f32 v[110:111], v[110:111], v[110:111]
	v_pk_mul_f32 v[176:177], v[106:107], v[106:107]
	v_pk_fma_f32 v[118:119], v[118:119], v[174:175], v[142:143] op_sel_hi:[1,0,1]
	v_pk_fma_f32 v[116:117], v[116:117], v[174:175], v[140:141] op_sel_hi:[1,0,1]
	v_pk_fma_f32 v[114:115], v[114:115], v[174:175], v[138:139] op_sel_hi:[1,0,1]
	v_pk_fma_f32 v[112:113], v[112:113], v[174:175], v[136:137] op_sel_hi:[1,0,1]
	v_cvt_pk_bf16_f32 v104, v124, v125
	v_cvt_pk_bf16_f32 v105, v126, v127
	v_cvt_pk_bf16_f32 v106, v120, v121
	v_cvt_pk_bf16_f32 v107, v122, v123
	v_cvt_pk_bf16_f32 v108, v108, v109
	v_cvt_pk_bf16_f32 v109, v110, v111
	v_cvt_pk_bf16_f32 v110, v172, v173
	v_cvt_pk_bf16_f32 v111, v176, v177
	v_addc_co_u32_e32 v163, vcc, 0, v161, vcc
	v_max_f32_e32 v116, 0, v116
	v_max_f32_e32 v112, 0, v112
	v_max_f32_e32 v117, 0, v117
	global_store_dwordx4 v[160:161], v[104:107], off
	global_store_dwordx4 v[162:163], v[108:111], off
	v_max_f32_e32 v113, 0, v113
	v_pk_mul_f32 v[104:105], v[116:117], v[116:117]
	v_max_f32_e32 v108, 0, v118
	v_max_f32_e32 v110, 0, v114
	v_max_f32_e32 v109, 0, v119
	v_max_f32_e32 v111, 0, v115
	v_pk_mul_f32 v[106:107], v[112:113], v[112:113]
	v_pk_mul_f32 v[108:109], v[108:109], v[108:109]
	v_pk_mul_f32 v[110:111], v[110:111], v[110:111]
	v_pk_fma_f32 v[100:101], v[100:101], v[174:175], v[132:133] op_sel_hi:[1,0,1]
	v_pk_fma_f32 v[96:97], v[96:97], v[174:175], v[128:129] op_sel_hi:[1,0,1]
	v_cvt_pk_bf16_f32 v104, v104, v105
	v_cvt_pk_bf16_f32 v105, v108, v109
	v_cvt_pk_bf16_f32 v106, v106, v107
	v_cvt_pk_bf16_f32 v107, v110, v111
	v_pk_fma_f32 v[102:103], v[102:103], v[174:175], v[134:135] op_sel_hi:[1,0,1]
	v_max_f32_e32 v100, 0, v100
	v_max_f32_e32 v96, 0, v96
	v_max_f32_e32 v101, 0, v101
	v_max_f32_e32 v97, 0, v97
	global_store_dwordx4 v[160:161], v[104:107], off offset:1024
	v_pk_mul_f32 v[100:101], v[100:101], v[100:101]
	v_pk_fma_f32 v[98:99], v[98:99], v[174:175], v[130:131] op_sel_hi:[1,0,1]
	v_pk_mul_f32 v[104:105], v[96:97], v[96:97]
	v_max_f32_e32 v96, 0, v102
	v_max_f32_e32 v97, 0, v103
	v_pk_mul_f32 v[102:103], v[96:97], v[96:97]
	v_cvt_pk_bf16_f32 v96, v100, v101
	ds_read2_b32 v[100:101], v170 offset0:32 offset1:48
	v_max_f32_e32 v98, 0, v98
	v_max_f32_e32 v99, 0, v99
	v_pk_mul_f32 v[106:107], v[98:99], v[98:99]
	v_cvt_pk_bf16_f32 v97, v102, v103
	s_waitcnt lgkmcnt(0)
	v_pk_fma_f32 v[88:89], v[88:89], v[100:101], v[136:137] op_sel_hi:[1,0,1]
	v_cvt_pk_bf16_f32 v98, v104, v105
	v_cvt_pk_bf16_f32 v99, v106, v107
	v_pk_fma_f32 v[94:95], v[94:95], v[100:101], v[142:143] op_sel_hi:[1,0,1]
	v_pk_fma_f32 v[92:93], v[92:93], v[100:101], v[140:141] op_sel_hi:[1,0,1]
	v_pk_fma_f32 v[90:91], v[90:91], v[100:101], v[138:139] op_sel_hi:[1,0,1]
	v_max_f32_e32 v88, 0, v88
	v_max_f32_e32 v89, 0, v89
	global_store_dwordx4 v[162:163], v[96:99], off offset:1024
	v_max_f32_e32 v92, 0, v92
	v_max_f32_e32 v93, 0, v93
	v_pk_mul_f32 v[96:97], v[88:89], v[88:89]
	v_max_f32_e32 v88, 0, v94
	v_max_f32_e32 v90, 0, v90
	v_max_f32_e32 v89, 0, v95
	v_max_f32_e32 v91, 0, v91
	v_pk_mul_f32 v[92:93], v[92:93], v[92:93]
	v_pk_mul_f32 v[94:95], v[88:89], v[88:89]
	v_pk_mul_f32 v[98:99], v[90:91], v[90:91]
	v_pk_fma_f32 v[80:81], v[80:81], v[100:101], v[128:129] op_sel_hi:[1,0,1]
	v_cvt_pk_bf16_f32 v88, v92, v93
	v_cvt_pk_bf16_f32 v89, v94, v95
	v_cvt_pk_bf16_f32 v90, v96, v97
	v_cvt_pk_bf16_f32 v91, v98, v99
	v_pk_fma_f32 v[86:87], v[86:87], v[100:101], v[134:135] op_sel_hi:[1,0,1]
	v_pk_fma_f32 v[84:85], v[84:85], v[100:101], v[132:133] op_sel_hi:[1,0,1]
	v_pk_fma_f32 v[82:83], v[82:83], v[100:101], v[130:131] op_sel_hi:[1,0,1]
	v_max_f32_e32 v80, 0, v80
	v_max_f32_e32 v81, 0, v81
	global_store_dwordx4 v[160:161], v[88:91], off offset:2048
	v_max_f32_e32 v84, 0, v84
	v_max_f32_e32 v85, 0, v85
	v_pk_mul_f32 v[88:89], v[80:81], v[80:81]
	v_max_f32_e32 v80, 0, v86
	v_max_f32_e32 v82, 0, v82
	v_max_f32_e32 v81, 0, v87
	v_max_f32_e32 v83, 0, v83
	v_pk_mul_f32 v[84:85], v[84:85], v[84:85]
	v_pk_mul_f32 v[86:87], v[80:81], v[80:81]
	v_pk_mul_f32 v[90:91], v[82:83], v[82:83]
	v_cvt_pk_bf16_f32 v80, v84, v85
	v_cvt_pk_bf16_f32 v81, v86, v87
	v_cvt_pk_bf16_f32 v82, v88, v89
	v_cvt_pk_bf16_f32 v83, v90, v91
	global_store_dwordx4 v[162:163], v[80:83], off offset:2048
	s_nop 1
	v_mov_b32_e32 v80, v101
	v_pk_fma_f32 v[72:73], v[72:73], v[80:81], v[136:137] op_sel_hi:[1,0,1]
	v_pk_fma_f32 v[78:79], v[78:79], v[80:81], v[142:143] op_sel_hi:[1,0,1]
	v_pk_fma_f32 v[76:77], v[76:77], v[80:81], v[140:141] op_sel_hi:[1,0,1]
	v_pk_fma_f32 v[74:75], v[74:75], v[80:81], v[138:139] op_sel_hi:[1,0,1]
	v_max_f32_e32 v72, 0, v72
	v_max_f32_e32 v73, 0, v73
	v_max_f32_e32 v76, 0, v76
	v_max_f32_e32 v77, 0, v77
	v_pk_mul_f32 v[82:83], v[72:73], v[72:73]
	v_max_f32_e32 v72, 0, v78
	v_max_f32_e32 v74, 0, v74
	v_max_f32_e32 v73, 0, v79
	v_max_f32_e32 v75, 0, v75
	v_pk_mul_f32 v[76:77], v[76:77], v[76:77]
	v_pk_mul_f32 v[78:79], v[72:73], v[72:73]
	v_pk_mul_f32 v[84:85], v[74:75], v[74:75]
	v_pk_fma_f32 v[68:69], v[68:69], v[80:81], v[132:133] op_sel_hi:[1,0,1]
	v_pk_fma_f32 v[64:65], v[64:65], v[80:81], v[128:129] op_sel_hi:[1,0,1]
	v_cvt_pk_bf16_f32 v72, v76, v77
	v_cvt_pk_bf16_f32 v73, v78, v79
	v_cvt_pk_bf16_f32 v74, v82, v83
	v_cvt_pk_bf16_f32 v75, v84, v85
	v_pk_fma_f32 v[70:71], v[70:71], v[80:81], v[134:135] op_sel_hi:[1,0,1]
	v_max_f32_e32 v68, 0, v68
	v_max_f32_e32 v64, 0, v64
	v_max_f32_e32 v69, 0, v69
	v_max_f32_e32 v65, 0, v65
	global_store_dwordx4 v[160:161], v[72:75], off offset:3072
	v_pk_mul_f32 v[68:69], v[68:69], v[68:69]
	v_pk_fma_f32 v[66:67], v[66:67], v[80:81], v[130:131] op_sel_hi:[1,0,1]
	v_pk_mul_f32 v[72:73], v[64:65], v[64:65]
	v_max_f32_e32 v64, 0, v70
	v_max_f32_e32 v65, 0, v71
	v_pk_mul_f32 v[70:71], v[64:65], v[64:65]
	v_cvt_pk_bf16_f32 v64, v68, v69
	ds_read2_b32 v[68:69], v170 offset0:128 offset1:144
	v_max_f32_e32 v66, 0, v66
	v_max_f32_e32 v67, 0, v67
	v_pk_mul_f32 v[74:75], v[66:67], v[66:67]
	v_cvt_pk_bf16_f32 v65, v70, v71
	s_waitcnt lgkmcnt(0)
	v_pk_fma_f32 v[60:61], v[60:61], v[68:69], v[140:141] op_sel_hi:[1,0,1]
	v_pk_fma_f32 v[56:57], v[56:57], v[68:69], v[136:137] op_sel_hi:[1,0,1]
	v_cvt_pk_bf16_f32 v66, v72, v73
	v_cvt_pk_bf16_f32 v67, v74, v75
	v_pk_fma_f32 v[62:63], v[62:63], v[68:69], v[142:143] op_sel_hi:[1,0,1]
	v_pk_fma_f32 v[58:59], v[58:59], v[68:69], v[138:139] op_sel_hi:[1,0,1]
	v_max_f32_e32 v60, 0, v60
	v_max_f32_e32 v56, 0, v56
	v_max_f32_e32 v61, 0, v61
	v_max_f32_e32 v57, 0, v57
	global_store_dwordx4 v[162:163], v[64:67], off offset:3072
	v_pk_mul_f32 v[60:61], v[60:61], v[60:61]
	v_max_f32_e32 v58, 0, v58
	v_pk_mul_f32 v[64:65], v[56:57], v[56:57]
	v_max_f32_e32 v56, 0, v62
	v_max_f32_e32 v57, 0, v63
	v_max_f32_e32 v59, 0, v59
	v_pk_mul_f32 v[62:63], v[56:57], v[56:57]
	v_pk_mul_f32 v[66:67], v[58:59], v[58:59]
	v_cvt_pk_bf16_f32 v56, v60, v61
	v_add_co_u32_e32 v60, vcc, s51, v160
	v_pk_fma_f32 v[52:53], v[52:53], v[68:69], v[132:133] op_sel_hi:[1,0,1]
	v_pk_fma_f32 v[48:49], v[48:49], v[68:69], v[128:129] op_sel_hi:[1,0,1]
	v_cvt_pk_bf16_f32 v57, v62, v63
	v_cvt_pk_bf16_f32 v58, v64, v65
	v_cvt_pk_bf16_f32 v59, v66, v67
	v_addc_co_u32_e32 v61, vcc, 0, v161, vcc
	v_pk_fma_f32 v[54:55], v[54:55], v[68:69], v[134:135] op_sel_hi:[1,0,1]
	v_pk_fma_f32 v[50:51], v[50:51], v[68:69], v[130:131] op_sel_hi:[1,0,1]
	v_max_f32_e32 v52, 0, v52
	v_max_f32_e32 v48, 0, v48
	v_max_f32_e32 v53, 0, v53
	v_max_f32_e32 v49, 0, v49
	global_store_dwordx4 v[60:61], v[56:59], off
	v_pk_mul_f32 v[52:53], v[52:53], v[52:53]
	v_max_f32_e32 v50, 0, v50
	v_pk_mul_f32 v[56:57], v[48:49], v[48:49]
	v_max_f32_e32 v48, 0, v54
	v_max_f32_e32 v49, 0, v55
	v_max_f32_e32 v51, 0, v51
	v_pk_mul_f32 v[54:55], v[48:49], v[48:49]
	v_pk_mul_f32 v[58:59], v[50:51], v[50:51]
	v_cvt_pk_bf16_f32 v48, v52, v53
	v_add_co_u32_e32 v52, vcc, s50, v160
	v_cvt_pk_bf16_f32 v49, v54, v55
	v_cvt_pk_bf16_f32 v50, v56, v57
	v_cvt_pk_bf16_f32 v51, v58, v59
	v_addc_co_u32_e32 v53, vcc, 0, v161, vcc
	global_store_dwordx4 v[52:53], v[48:51], off
	s_andn2_b64 vcc, exec, s[4:5]
	s_mov_b64 s[4:5], -1
	v_mov_b32_e32 v48, v69
	v_pk_fma_f32 v[40:41], v[40:41], v[48:49], v[136:137] op_sel_hi:[1,0,1]
	v_pk_fma_f32 v[46:47], v[46:47], v[48:49], v[142:143] op_sel_hi:[1,0,1]
	v_pk_fma_f32 v[44:45], v[44:45], v[48:49], v[140:141] op_sel_hi:[1,0,1]
	v_pk_fma_f32 v[42:43], v[42:43], v[48:49], v[138:139] op_sel_hi:[1,0,1]
	v_max_f32_e32 v40, 0, v40
	v_max_f32_e32 v41, 0, v41
	v_max_f32_e32 v44, 0, v44
	v_max_f32_e32 v45, 0, v45
	v_pk_mul_f32 v[50:51], v[40:41], v[40:41]
	v_max_f32_e32 v40, 0, v46
	v_max_f32_e32 v42, 0, v42
	v_max_f32_e32 v41, 0, v47
	v_max_f32_e32 v43, 0, v43
	v_pk_mul_f32 v[44:45], v[44:45], v[44:45]
	v_pk_mul_f32 v[46:47], v[40:41], v[40:41]
	v_pk_mul_f32 v[54:55], v[42:43], v[42:43]
	v_pk_fma_f32 v[36:37], v[36:37], v[48:49], v[132:133] op_sel_hi:[1,0,1]
	v_pk_fma_f32 v[32:33], v[32:33], v[48:49], v[128:129] op_sel_hi:[1,0,1]
	v_cvt_pk_bf16_f32 v40, v44, v45
	v_cvt_pk_bf16_f32 v41, v46, v47
	v_cvt_pk_bf16_f32 v42, v50, v51
	v_cvt_pk_bf16_f32 v43, v54, v55
	v_pk_fma_f32 v[38:39], v[38:39], v[48:49], v[134:135] op_sel_hi:[1,0,1]
	v_max_f32_e32 v36, 0, v36
	v_max_f32_e32 v32, 0, v32
	v_max_f32_e32 v37, 0, v37
	v_max_f32_e32 v33, 0, v33
	global_store_dwordx4 v[60:61], v[40:43], off offset:1024
	v_pk_mul_f32 v[36:37], v[36:37], v[36:37]
	v_pk_fma_f32 v[34:35], v[34:35], v[48:49], v[130:131] op_sel_hi:[1,0,1]
	v_pk_mul_f32 v[40:41], v[32:33], v[32:33]
	v_max_f32_e32 v32, 0, v38
	v_max_f32_e32 v33, 0, v39
	v_pk_mul_f32 v[38:39], v[32:33], v[32:33]
	v_cvt_pk_bf16_f32 v32, v36, v37
	ds_read2_b32 v[36:37], v170 offset0:160 offset1:176
	v_max_f32_e32 v34, 0, v34
	v_max_f32_e32 v35, 0, v35
	v_pk_mul_f32 v[42:43], v[34:35], v[34:35]
	v_cvt_pk_bf16_f32 v33, v38, v39
	s_waitcnt lgkmcnt(0)
	v_pk_fma_f32 v[24:25], v[24:25], v[36:37], v[136:137] op_sel_hi:[1,0,1]
	v_cvt_pk_bf16_f32 v34, v40, v41
	v_cvt_pk_bf16_f32 v35, v42, v43
	v_pk_fma_f32 v[30:31], v[30:31], v[36:37], v[142:143] op_sel_hi:[1,0,1]
	v_pk_fma_f32 v[28:29], v[28:29], v[36:37], v[140:141] op_sel_hi:[1,0,1]
	v_pk_fma_f32 v[26:27], v[26:27], v[36:37], v[138:139] op_sel_hi:[1,0,1]
	v_max_f32_e32 v24, 0, v24
	v_max_f32_e32 v25, 0, v25
	global_store_dwordx4 v[52:53], v[32:35], off offset:1024
	v_max_f32_e32 v28, 0, v28
	v_max_f32_e32 v29, 0, v29
	v_pk_mul_f32 v[32:33], v[24:25], v[24:25]
	v_max_f32_e32 v24, 0, v30
	v_max_f32_e32 v26, 0, v26
	v_max_f32_e32 v25, 0, v31
	v_max_f32_e32 v27, 0, v27
	v_pk_mul_f32 v[28:29], v[28:29], v[28:29]
	v_pk_mul_f32 v[30:31], v[24:25], v[24:25]
	v_pk_mul_f32 v[34:35], v[26:27], v[26:27]
	v_pk_fma_f32 v[16:17], v[16:17], v[36:37], v[128:129] op_sel_hi:[1,0,1]
	v_cvt_pk_bf16_f32 v24, v28, v29
	v_cvt_pk_bf16_f32 v25, v30, v31
	v_cvt_pk_bf16_f32 v26, v32, v33
	v_cvt_pk_bf16_f32 v27, v34, v35
	v_pk_fma_f32 v[22:23], v[22:23], v[36:37], v[134:135] op_sel_hi:[1,0,1]
	v_pk_fma_f32 v[20:21], v[20:21], v[36:37], v[132:133] op_sel_hi:[1,0,1]
	v_pk_fma_f32 v[18:19], v[18:19], v[36:37], v[130:131] op_sel_hi:[1,0,1]
	v_max_f32_e32 v16, 0, v16
	v_max_f32_e32 v17, 0, v17
	global_store_dwordx4 v[60:61], v[24:27], off offset:2048
	v_max_f32_e32 v20, 0, v20
	v_max_f32_e32 v21, 0, v21
	v_pk_mul_f32 v[24:25], v[16:17], v[16:17]
	v_max_f32_e32 v16, 0, v22
	v_max_f32_e32 v18, 0, v18
	v_max_f32_e32 v17, 0, v23
	v_max_f32_e32 v19, 0, v19
	v_pk_mul_f32 v[20:21], v[20:21], v[20:21]
	v_pk_mul_f32 v[22:23], v[16:17], v[16:17]
	v_pk_mul_f32 v[26:27], v[18:19], v[18:19]
	v_cvt_pk_bf16_f32 v16, v20, v21
	v_cvt_pk_bf16_f32 v17, v22, v23
	v_cvt_pk_bf16_f32 v18, v24, v25
	v_cvt_pk_bf16_f32 v19, v26, v27
	global_store_dwordx4 v[52:53], v[16:19], off offset:2048
	s_nop 1
	v_mov_b32_e32 v16, v37
	v_pk_fma_f32 v[8:9], v[8:9], v[16:17], v[136:137] op_sel_hi:[1,0,1]
	v_pk_fma_f32 v[14:15], v[14:15], v[16:17], v[142:143] op_sel_hi:[1,0,1]
	v_pk_fma_f32 v[12:13], v[12:13], v[16:17], v[140:141] op_sel_hi:[1,0,1]
	v_pk_fma_f32 v[10:11], v[10:11], v[16:17], v[138:139] op_sel_hi:[1,0,1]
	v_max_f32_e32 v8, 0, v8
	v_max_f32_e32 v9, 0, v9
	v_max_f32_e32 v12, 0, v12
	v_max_f32_e32 v13, 0, v13
	v_pk_mul_f32 v[18:19], v[8:9], v[8:9]
	v_max_f32_e32 v8, 0, v14
	v_max_f32_e32 v10, 0, v10
	v_max_f32_e32 v9, 0, v15
	v_max_f32_e32 v11, 0, v11
	v_pk_mul_f32 v[12:13], v[12:13], v[12:13]
	v_pk_mul_f32 v[14:15], v[8:9], v[8:9]
	v_pk_mul_f32 v[20:21], v[10:11], v[10:11]
	v_pk_fma_f32 v[0:1], v[0:1], v[16:17], v[128:129] op_sel_hi:[1,0,1]
	v_cvt_pk_bf16_f32 v8, v12, v13
	v_cvt_pk_bf16_f32 v9, v14, v15
	v_cvt_pk_bf16_f32 v10, v18, v19
	v_cvt_pk_bf16_f32 v11, v20, v21
	v_pk_fma_f32 v[6:7], v[6:7], v[16:17], v[134:135] op_sel_hi:[1,0,1]
	v_pk_fma_f32 v[4:5], v[4:5], v[16:17], v[132:133] op_sel_hi:[1,0,1]
	v_pk_fma_f32 v[2:3], v[2:3], v[16:17], v[130:131] op_sel_hi:[1,0,1]
	v_max_f32_e32 v0, 0, v0
	v_max_f32_e32 v1, 0, v1
	global_store_dwordx4 v[60:61], v[8:11], off offset:3072
	v_max_f32_e32 v4, 0, v4
	v_max_f32_e32 v5, 0, v5
	v_pk_mul_f32 v[8:9], v[0:1], v[0:1]
	v_max_f32_e32 v0, 0, v6
	v_max_f32_e32 v2, 0, v2
	v_max_f32_e32 v1, 0, v7
	v_max_f32_e32 v3, 0, v3
	v_pk_mul_f32 v[4:5], v[4:5], v[4:5]
	v_pk_mul_f32 v[6:7], v[0:1], v[0:1]
	v_pk_mul_f32 v[10:11], v[2:3], v[2:3]
	v_cvt_pk_bf16_f32 v0, v4, v5
	v_cvt_pk_bf16_f32 v1, v6, v7
	v_cvt_pk_bf16_f32 v2, v8, v9
	v_cvt_pk_bf16_f32 v3, v10, v11
	global_store_dwordx4 v[52:53], v[0:3], off offset:3072
	s_cbranch_vccnz .LBB0_560
	s_andn2_b64 vcc, exec, s[8:9]
	s_cbranch_vccnz .LBB0_559
	s_branch .LBB0_559
